# combo1
# speedup vs baseline: 1.0069x; 1.0058x over previous
.LBB0_249:
	s_ashr_i32 s21, s20, 31
	s_lshl_b64 s[4:5], s[20:21], 18
	s_add_u32 s22, s45, s4
	s_addc_u32 s23, s76, s5
	s_ashr_i32 s19, s18, 31
	s_lshl_b64 s[26:27], s[18:19], 18
	v_readlane_b32 s8, v253, 30
	v_readlane_b32 s9, v253, 31
	s_add_u32 s24, s8, s26
	s_addc_u32 s25, s9, s27
	s_ashr_i32 s13, s12, 31
	s_lshl_b64 s[4:5], s[12:13], 18
	s_add_u32 s6, s45, s4
	s_addc_u32 s7, s76, s5
	s_ashr_i32 s15, s14, 31
	s_lshl_b64 s[4:5], s[14:15], 18
	s_add_u32 s8, s8, s4
	s_addc_u32 s9, s9, s5
	s_and_b64 s[4:5], s[16:17], exec
	s_cselect_b32 s15, s7, s23
	s_cselect_b32 s19, s6, s22
	s_cselect_b32 s21, s9, s25
	s_cselect_b32 s78, s8, s24
	s_lshl_b32 s13, s18, 7
	s_sub_i32 s4, s20, 35
	s_cmp_gt_u32 s4, 7
	s_mov_b64 s[4:5], -1
	s_cbranch_scc0 .LBB0_789
	v_mov_b32_e32 v98, v180
	s_mov_b32 s4, 0x1ffffc0
	v_lshlrev_b32_e32 v0, 3, v98
	s_waitcnt vmcnt(23)
	v_ashrrev_i32_e32 v5, 3, v98
	v_and_b32_e32 v0, 56, v0
	v_lshl_or_b32 v0, v5, 10, v0
	v_and_b32_e32 v2, 15, v98
	v_lshrrev_b32_e32 v3, 4, v98
	s_waitcnt vmcnt(22)
	v_lshrrev_b32_e32 v6, 1, v98
	v_bfe_u32 v7, v98, 1, 3
	v_lshlrev_b64 v[168:169], 1, v[0:1]
	v_xor_b32_e32 v8, v3, v98
	v_bitop3_b32 v99, v3, v7, 3 bitop3:0x6c
	v_and_or_b32 v101, v6, s4, v2
	v_lshl_add_u64 v[2:3], s[22:23], 0, v[168:169]
	v_bfe_u32 v4, v98, 4, 2
	s_waitcnt vmcnt(21)
	v_add_co_u32_e32 v10, vcc, s71, v2
	v_bitop3_b32 v100, v4, v7, 4 bitop3:0x36
	v_lshl_add_u64 v[6:7], s[24:25], 0, v[168:169]
	v_addc_co_u32_e32 v11, vcc, 0, v3, vcc
	s_waitcnt vmcnt(20)
	v_add_co_u32_e32 v14, vcc, s71, v6
	v_lshlrev_b32_e32 v0, 4, v8
	s_nop 0
	v_addc_co_u32_e32 v15, vcc, 0, v7, vcc
	s_waitcnt vmcnt(19)
	v_add_co_u32_e32 v18, vcc, s0, v2
	v_and_b32_e32 v0, 0x70, v0
	s_nop 0
	v_addc_co_u32_e32 v19, vcc, 0, v3, vcc
	s_waitcnt vmcnt(18)
	v_add_co_u32_e32 v22, vcc, s0, v6
	v_lshl_or_b32 v167, v5, 7, v0
	s_nop 0
	v_addc_co_u32_e32 v23, vcc, 0, v7, vcc
	s_waitcnt vmcnt(17)
	v_add_co_u32_e32 v26, vcc, s1, v2
	s_waitcnt vmcnt(7)
	ds_write_b128 v167, v[34:37]
	s_waitcnt vmcnt(6)
	ds_write_b128 v167, v[38:41] offset:16384
	s_waitcnt vmcnt(5)
	ds_write_b128 v167, v[42:45] offset:4096
	s_waitcnt vmcnt(4)
	ds_write_b128 v167, v[46:49] offset:20480
	s_waitcnt vmcnt(3)
	ds_write_b128 v167, v[50:53] offset:8192
	s_waitcnt vmcnt(2)
	ds_write_b128 v167, v[54:57] offset:24576
	s_waitcnt vmcnt(1)
	ds_write_b128 v167, v[58:61] offset:12288
	s_waitcnt vmcnt(0)
	ds_write_b128 v167, v[62:65] offset:28672
	v_addc_co_u32_e32 v27, vcc, 0, v3, vcc
	v_add_co_u32_e32 v30, vcc, s1, v6
	v_lshlrev_b32_e32 v98, 7, v98
	s_nop 0
	v_addc_co_u32_e32 v31, vcc, 0, v7, vcc
	global_load_dwordx4 v[66:69], v[2:3], off offset:128
	s_nop 0
	global_load_dwordx4 v[2:5], v[2:3], off offset:256
	s_nop 0
	global_load_dwordx4 v[70:73], v[6:7], off offset:128
	s_nop 0
	global_load_dwordx4 v[6:9], v[6:7], off offset:256
	s_nop 0
	global_load_dwordx4 v[74:77], v[10:11], off offset:128
	s_nop 0
	global_load_dwordx4 v[10:13], v[10:11], off offset:256
	s_nop 0
	global_load_dwordx4 v[78:81], v[14:15], off offset:128
	s_nop 0
	global_load_dwordx4 v[14:17], v[14:15], off offset:256
	s_nop 0
	global_load_dwordx4 v[82:85], v[18:19], off offset:128
	s_nop 0
	global_load_dwordx4 v[18:21], v[18:19], off offset:256
	s_nop 0
	global_load_dwordx4 v[86:89], v[22:23], off offset:128
	s_nop 0
	global_load_dwordx4 v[22:25], v[22:23], off offset:256
	s_nop 0
	global_load_dwordx4 v[90:93], v[26:27], off offset:128
	s_nop 0
	global_load_dwordx4 v[26:29], v[26:27], off offset:256
	s_nop 0
	global_load_dwordx4 v[94:97], v[30:31], off offset:128
	s_nop 0
	global_load_dwordx4 v[30:33], v[30:31], off offset:256
	v_lshlrev_b32_e32 v0, 7, v101
	v_lshlrev_b32_e32 v99, 4, v99
	v_and_b32_e32 v98, 0x2780, v98
	v_or_b32_e32 v165, v0, v99
	v_or_b32_e32 v170, v98, v99
	v_lshlrev_b32_e32 v99, 4, v100
	s_add_u32 s6, s68, s26
	v_mov_b32_e32 v150, 0
	s_mov_b32 s10, 0
	v_or_b32_e32 v0, v0, v99
	v_or_b32_e32 v163, v98, v99
	s_addc_u32 s7, s69, s27
	s_movk_i32 s11, 0x100
	s_mov_b64 s[8:9], s[22:23]
	v_mov_b32_e32 v151, v150
	v_mov_b32_e32 v152, v150
	v_mov_b32_e32 v153, v150
	v_mov_b32_e32 v154, v150
	v_mov_b32_e32 v155, v150
	v_mov_b32_e32 v156, v150
	v_mov_b32_e32 v157, v150
	v_mov_b32_e32 v158, v150
	v_mov_b32_e32 v159, v150
	v_mov_b32_e32 v160, v150
	v_mov_b32_e32 v161, v150
	v_mov_b32_e32 v98, v150
	v_mov_b32_e32 v99, v150
	v_mov_b32_e32 v100, v150
	v_mov_b32_e32 v101, v150
	v_mov_b32_e32 v130, v150
	v_mov_b32_e32 v131, v150
	v_mov_b32_e32 v132, v150
	v_mov_b32_e32 v133, v150
	v_mov_b32_e32 v134, v150
	v_mov_b32_e32 v135, v150
	v_mov_b32_e32 v136, v150
	v_mov_b32_e32 v137, v150
	v_mov_b32_e32 v122, v150
	v_mov_b32_e32 v123, v150
	v_mov_b32_e32 v124, v150
	v_mov_b32_e32 v125, v150
	v_mov_b32_e32 v110, v150
	v_mov_b32_e32 v111, v150
	v_mov_b32_e32 v112, v150
	v_mov_b32_e32 v113, v150
	v_mov_b32_e32 v114, v150
	v_mov_b32_e32 v115, v150
	v_mov_b32_e32 v116, v150
	v_mov_b32_e32 v117, v150
	v_mov_b32_e32 v106, v150
	v_mov_b32_e32 v107, v150
	v_mov_b32_e32 v108, v150
	v_mov_b32_e32 v109, v150
	v_mov_b32_e32 v102, v150
	v_mov_b32_e32 v103, v150
	v_mov_b32_e32 v104, v150
	v_mov_b32_e32 v105, v150
	v_mov_b32_e32 v118, v150
	v_mov_b32_e32 v119, v150
	v_mov_b32_e32 v120, v150
	v_mov_b32_e32 v121, v150
	v_mov_b32_e32 v138, v150
	v_mov_b32_e32 v139, v150
	v_mov_b32_e32 v140, v150
	v_mov_b32_e32 v141, v150
	v_mov_b32_e32 v142, v150
	v_mov_b32_e32 v143, v150
	v_mov_b32_e32 v144, v150
	v_mov_b32_e32 v145, v150
	v_mov_b32_e32 v146, v150
	v_mov_b32_e32 v147, v150
	v_mov_b32_e32 v148, v150
	v_mov_b32_e32 v149, v150
	v_mov_b32_e32 v126, v150
	v_mov_b32_e32 v127, v150
	v_mov_b32_e32 v128, v150
	v_mov_b32_e32 v129, v150
	s_mov_b32 s31, 0x1cb24000
	s_mov_b32 s34, 0x1cb34000
	s_mov_b32 s35, 0x1cb44000
	s_mov_b32 s36, 0x1cb54000
	s_waitcnt lgkmcnt(0)
	s_barrier
	ds_read_b128 v[236:239], v165
	ds_read_b128 v[240:243], v170 offset:16384
	ds_read_b128 v[198:201], v165 offset:2048
	ds_read_b128 v[244:247], v170 offset:18432
	ds_read_b128 v[206:209], v170 offset:20480
	ds_read_b128 v[210:213], v170 offset:22528
	ds_read_b128 v[188:191], v165 offset:4096
	ds_read_b128 v[192:195], v165 offset:6144
.LBB0_251:
	s_cmp_lt_u32 s10, 12
	s_waitcnt lgkmcnt(6)
	v_mfma_f32_16x16x32_bf16 v[126:129], v[236:239], v[240:243], v[126:129]
	s_cselect_b64 s[4:5], -1, 0
	s_waitcnt lgkmcnt(4)
	v_mfma_f32_16x16x32_bf16 v[146:149], v[236:239], v[244:247], v[146:149]
	s_waitcnt lgkmcnt(3)
	v_mfma_f32_16x16x32_bf16 v[142:145], v[236:239], v[206:209], v[142:145]
	s_waitcnt lgkmcnt(2)
	v_mfma_f32_16x16x32_bf16 v[138:141], v[236:239], v[210:213], v[138:141]
	v_mfma_f32_16x16x32_bf16 v[118:121], v[198:201], v[240:243], v[118:121]
	v_mfma_f32_16x16x32_bf16 v[102:105], v[198:201], v[244:247], v[102:105]
	v_mfma_f32_16x16x32_bf16 v[106:109], v[198:201], v[206:209], v[106:109]
	v_mfma_f32_16x16x32_bf16 v[114:117], v[198:201], v[210:213], v[114:117]
	s_waitcnt lgkmcnt(1)
	v_mfma_f32_16x16x32_bf16 v[110:113], v[188:191], v[240:243], v[110:113]
	v_mfma_f32_16x16x32_bf16 v[122:125], v[188:191], v[244:247], v[122:125]
	v_mfma_f32_16x16x32_bf16 v[134:137], v[188:191], v[206:209], v[134:137]
	v_mfma_f32_16x16x32_bf16 v[130:133], v[188:191], v[210:213], v[130:133]
	s_waitcnt lgkmcnt(0)
	v_mfma_f32_16x16x32_bf16 v[98:101], v[192:195], v[240:243], v[98:101]
	v_mfma_f32_16x16x32_bf16 v[158:161], v[192:195], v[244:247], v[158:161]
	ds_read_b128 v[172:175], v163 offset:16384
	ds_read_b128 v[176:179], v0
	ds_read_b128 v[202:205], v0 offset:2048
	v_mfma_f32_16x16x32_bf16 v[154:157], v[192:195], v[206:209], v[154:157]
	ds_read_b128 v[206:209], v163 offset:18432
	ds_read_b128 v[214:217], v0 offset:4096
	ds_read_b128 v[218:221], v0 offset:6144
	v_mfma_f32_16x16x32_bf16 v[150:153], v[192:195], v[210:213], v[150:153]
	ds_read_b128 v[198:201], v163 offset:20480
	ds_read_b128 v[210:213], v163 offset:22528
	s_waitcnt vmcnt(15)
	ds_write_b128 v167, v[66:69] offset:32768
	s_waitcnt vmcnt(13)
	ds_write_b128 v167, v[70:73] offset:49152
	s_waitcnt vmcnt(11)
	ds_write_b128 v167, v[74:77] offset:36864
	s_waitcnt vmcnt(9)
	ds_write_b128 v167, v[78:81] offset:53248
	v_lshl_add_u64 v[72:73], s[6:7], 0, v[168:169]
	v_add_co_u32_e32 v74, vcc, s31, v72
	v_lshl_add_u64 v[70:71], s[8:9], 0, v[168:169]
	s_nop 0
	v_addc_co_u32_e32 v75, vcc, 0, v73, vcc
	v_add_co_u32_e32 v76, vcc, s71, v70
	s_waitcnt vmcnt(7)
	ds_write_b128 v167, v[82:85] offset:40960
	s_waitcnt vmcnt(5)
	ds_write_b128 v167, v[86:89] offset:57344
	s_waitcnt vmcnt(3)
	ds_write_b128 v167, v[90:93] offset:45056
	v_addc_co_u32_e32 v77, vcc, 0, v71, vcc
	v_add_co_u32_e32 v78, vcc, s34, v72
	s_waitcnt vmcnt(1)
	ds_write_b128 v167, v[94:97] offset:61440
	v_addc_co_u32_e32 v79, vcc, 0, v73, vcc
	v_add_co_u32_e32 v82, vcc, s0, v70
	s_waitcnt lgkmcnt(14)
	v_mfma_f32_16x16x32_bf16 v[126:129], v[176:179], v[172:175], v[126:129]
	v_addc_co_u32_e32 v83, vcc, 0, v71, vcc
	v_add_co_u32_e32 v86, vcc, s35, v72
	global_load_dwordx4 v[66:69], v[70:71], off offset:384
	s_nop 0
	v_addc_co_u32_e32 v87, vcc, 0, v73, vcc
	v_add_co_u32_e32 v90, vcc, s1, v70
	s_waitcnt lgkmcnt(13)
	v_mfma_f32_16x16x32_bf16 v[118:121], v[202:205], v[172:175], v[118:121]
	v_addc_co_u32_e32 v91, vcc, 0, v71, vcc
	v_add_co_u32_e32 v94, vcc, s36, v72
	s_waitcnt lgkmcnt(11)
	v_mfma_f32_16x16x32_bf16 v[110:113], v[214:217], v[172:175], v[110:113]
	v_addc_co_u32_e32 v95, vcc, 0, v73, vcc
	global_load_dwordx4 v[70:73], v[74:75], off offset:384
	s_nop 0
	global_load_dwordx4 v[74:77], v[76:77], off offset:384
	s_nop 0
	global_load_dwordx4 v[78:81], v[78:79], off offset:384
	s_nop 0
	global_load_dwordx4 v[82:85], v[82:83], off offset:384
	s_waitcnt lgkmcnt(10)
	v_mfma_f32_16x16x32_bf16 v[98:101], v[218:221], v[172:175], v[98:101]
	global_load_dwordx4 v[86:89], v[86:87], off offset:384
	s_nop 0
	global_load_dwordx4 v[90:93], v[90:91], off offset:384
	s_nop 0
	global_load_dwordx4 v[94:97], v[94:95], off offset:384
	s_waitcnt lgkmcnt(0)
	s_barrier
	ds_read_b128 v[172:175], v165 offset:32768
	v_mfma_f32_16x16x32_bf16 v[146:149], v[176:179], v[206:209], v[146:149]
	s_and_b64 vcc, s[4:5], exec
	s_cselect_b32 s5, s23, s15
	s_cselect_b32 s4, s22, s19
	v_mfma_f32_16x16x32_bf16 v[142:145], v[176:179], v[198:201], v[142:145]
	s_cselect_b32 s29, s25, s21
	s_cselect_b32 s28, s24, s78
	s_and_b32 s30, s11, 0x380
	v_mfma_f32_16x16x32_bf16 v[138:141], v[176:179], v[210:213], v[138:141]
	s_lshl_b32 s64, s30, 1
	s_add_i32 s10, s10, 2
	s_add_u32 s6, s6, 0x100
	v_mfma_f32_16x16x32_bf16 v[102:105], v[202:205], v[206:209], v[102:105]
	s_addc_u32 s7, s7, 0
	s_add_u32 s8, s8, 0x100
	s_addc_u32 s9, s9, 0
	v_mfma_f32_16x16x32_bf16 v[106:109], v[202:205], v[198:201], v[106:109]
	s_addk_i32 s11, 0x80
	v_mfma_f32_16x16x32_bf16 v[114:117], v[202:205], v[210:213], v[114:117]
	v_mfma_f32_16x16x32_bf16 v[122:125], v[214:217], v[206:209], v[122:125]
	v_mfma_f32_16x16x32_bf16 v[134:137], v[214:217], v[198:201], v[134:137]
	v_mfma_f32_16x16x32_bf16 v[130:133], v[214:217], v[210:213], v[130:133]
	v_mfma_f32_16x16x32_bf16 v[158:161], v[218:221], v[206:209], v[158:161]
	v_mfma_f32_16x16x32_bf16 v[154:157], v[218:221], v[198:201], v[154:157]
	ds_read_b128 v[176:179], v170 offset:49152
	ds_read_b128 v[198:201], v165 offset:34816
	ds_read_b128 v[202:205], v170 offset:51200
	v_mfma_f32_16x16x32_bf16 v[150:153], v[218:221], v[210:213], v[150:153]
	ds_read_b128 v[206:209], v170 offset:53248
	ds_read_b128 v[210:213], v170 offset:55296
	ds_read_b128 v[188:191], v165 offset:36864
	ds_read_b128 v[192:195], v165 offset:38912
	s_waitcnt lgkmcnt(6)
	v_mfma_f32_16x16x32_bf16 v[126:129], v[172:175], v[176:179], v[126:129]
	s_waitcnt lgkmcnt(4)
	v_mfma_f32_16x16x32_bf16 v[146:149], v[172:175], v[202:205], v[146:149]
	s_waitcnt lgkmcnt(3)
	v_mfma_f32_16x16x32_bf16 v[142:145], v[172:175], v[206:209], v[142:145]
	s_waitcnt lgkmcnt(2)
	v_mfma_f32_16x16x32_bf16 v[138:141], v[172:175], v[210:213], v[138:141]
	v_mfma_f32_16x16x32_bf16 v[118:121], v[198:201], v[176:179], v[118:121]
	v_mfma_f32_16x16x32_bf16 v[102:105], v[198:201], v[202:205], v[102:105]
	v_mfma_f32_16x16x32_bf16 v[106:109], v[198:201], v[206:209], v[106:109]
	v_mfma_f32_16x16x32_bf16 v[114:117], v[198:201], v[210:213], v[114:117]
	ds_read_b128 v[214:217], v0 offset:32768
	s_waitcnt lgkmcnt(2)
	v_mfma_f32_16x16x32_bf16 v[110:113], v[188:191], v[176:179], v[110:113]
	v_mfma_f32_16x16x32_bf16 v[122:125], v[188:191], v[202:205], v[122:125]
	v_mfma_f32_16x16x32_bf16 v[134:137], v[188:191], v[206:209], v[134:137]
	v_mfma_f32_16x16x32_bf16 v[130:133], v[188:191], v[210:213], v[130:133]
	ds_read_b128 v[172:175], v0 offset:34816
	ds_read_b128 v[218:221], v163 offset:49152
	ds_read_b128 v[222:225], v163 offset:51200
	s_waitcnt lgkmcnt(4)
	v_mfma_f32_16x16x32_bf16 v[98:101], v[192:195], v[176:179], v[98:101]
	ds_read_b128 v[176:179], v163 offset:53248
	ds_read_b128 v[226:229], v0 offset:36864
	ds_read_b128 v[230:233], v0 offset:38912
	v_mfma_f32_16x16x32_bf16 v[158:161], v[192:195], v[202:205], v[158:161]
	ds_read_b128 v[202:205], v163 offset:55296
	ds_write_b128 v167, v[2:5]
	ds_write_b128 v167, v[6:9] offset:16384
	v_lshl_add_u64 v[2:3], s[4:5], 0, v[168:169]
	ds_write_b128 v167, v[10:13] offset:4096
	ds_write_b128 v167, v[14:17] offset:20480
	ds_write_b128 v167, v[18:21] offset:8192
	v_lshl_add_u64 v[10:11], v[2:3], 0, s[64:65]
	v_lshl_add_u64 v[4:5], s[28:29], 0, v[168:169]
	v_add_co_u32_e64 v14, s[4:5], s71, v10
	v_lshl_add_u64 v[12:13], v[4:5], 0, s[64:65]
	s_nop 0
	v_addc_co_u32_e64 v15, s[4:5], 0, v11, s[4:5]
	v_add_co_u32_e64 v16, s[4:5], s71, v12
	ds_write_b128 v167, v[22:25] offset:24576
	ds_write_b128 v167, v[26:29] offset:12288
	s_waitcnt vmcnt(8)
	ds_write_b128 v167, v[30:33] offset:28672
	v_addc_co_u32_e64 v17, s[4:5], 0, v13, s[4:5]
	v_add_co_u32_e64 v18, s[4:5], s0, v10
	global_load_dwordx4 v[2:5], v[10:11], off
	s_nop 0
	v_addc_co_u32_e64 v19, s[4:5], 0, v11, s[4:5]
	v_add_co_u32_e64 v22, s[4:5], s0, v12
	global_load_dwordx4 v[6:9], v[12:13], off
	s_nop 0
	v_addc_co_u32_e64 v23, s[4:5], 0, v13, s[4:5]
	v_add_co_u32_e64 v26, s[4:5], s1, v10
	v_mfma_f32_16x16x32_bf16 v[154:157], v[192:195], v[206:209], v[154:157]
	s_nop 0
	v_addc_co_u32_e64 v27, s[4:5], 0, v11, s[4:5]
	v_add_co_u32_e64 v30, s[4:5], s1, v12
	v_mfma_f32_16x16x32_bf16 v[150:153], v[192:195], v[210:213], v[150:153]
	s_nop 0
	v_addc_co_u32_e64 v31, s[4:5], 0, v13, s[4:5]
	global_load_dwordx4 v[10:13], v[14:15], off
	s_nop 0
	global_load_dwordx4 v[14:17], v[16:17], off
	s_nop 0
	global_load_dwordx4 v[18:21], v[18:19], off
	s_nop 0
	global_load_dwordx4 v[22:25], v[22:23], off
	s_nop 0
	global_load_dwordx4 v[26:29], v[26:27], off
	s_waitcnt lgkmcnt(13)
	v_mfma_f32_16x16x32_bf16 v[126:129], v[214:217], v[218:221], v[126:129]
	global_load_dwordx4 v[30:33], v[30:31], off
	s_waitcnt lgkmcnt(0)
	s_barrier
	ds_read_b128 v[236:239], v165
	ds_read_b128 v[240:243], v170 offset:16384
	ds_read_b128 v[198:201], v165 offset:2048
	ds_read_b128 v[244:247], v170 offset:18432
	ds_read_b128 v[206:209], v170 offset:20480
	ds_read_b128 v[210:213], v170 offset:22528
	ds_read_b128 v[188:191], v165 offset:4096
	ds_read_b128 v[192:195], v165 offset:6144
	v_mfma_f32_16x16x32_bf16 v[146:149], v[214:217], v[222:225], v[146:149]
	v_mfma_f32_16x16x32_bf16 v[142:145], v[214:217], v[176:179], v[142:145]
	v_mfma_f32_16x16x32_bf16 v[138:141], v[214:217], v[202:205], v[138:141]
	v_mfma_f32_16x16x32_bf16 v[118:121], v[172:175], v[218:221], v[118:121]
	v_mfma_f32_16x16x32_bf16 v[102:105], v[172:175], v[222:225], v[102:105]
	v_mfma_f32_16x16x32_bf16 v[106:109], v[172:175], v[176:179], v[106:109]
	v_mfma_f32_16x16x32_bf16 v[114:117], v[172:175], v[202:205], v[114:117]
	v_mfma_f32_16x16x32_bf16 v[110:113], v[226:229], v[218:221], v[110:113]
	v_mfma_f32_16x16x32_bf16 v[122:125], v[226:229], v[222:225], v[122:125]
	v_mfma_f32_16x16x32_bf16 v[134:137], v[226:229], v[176:179], v[134:137]
	v_mfma_f32_16x16x32_bf16 v[130:133], v[226:229], v[202:205], v[130:133]
	v_mfma_f32_16x16x32_bf16 v[98:101], v[230:233], v[218:221], v[98:101]
	v_mfma_f32_16x16x32_bf16 v[158:161], v[230:233], v[222:225], v[158:161]
	v_mfma_f32_16x16x32_bf16 v[154:157], v[230:233], v[176:179], v[154:157]
	v_mfma_f32_16x16x32_bf16 v[150:153], v[230:233], v[202:205], v[150:153]
	s_cbranch_vccnz .LBB0_251
	ds_read_b128 v[172:175], v165
	ds_read_b128 v[176:179], v170 offset:16384
	ds_read_b128 v[198:201], v170 offset:18432
	ds_read_b128 v[202:205], v170 offset:20480
	ds_read_b128 v[206:209], v170 offset:22528
	s_cmp_lt_i32 s20, 8
	s_waitcnt lgkmcnt(3)
	v_mfma_f32_16x16x32_bf16 v[126:129], v[172:175], v[176:179], v[126:129]
	s_cselect_b64 s[4:5], -1, 0
	s_and_b64 vcc, exec, s[4:5]
	s_waitcnt lgkmcnt(2)
	v_mfma_f32_16x16x32_bf16 v[146:149], v[172:175], v[198:201], v[146:149]
	s_waitcnt lgkmcnt(1)
	v_mfma_f32_16x16x32_bf16 v[142:145], v[172:175], v[202:205], v[142:145]
	s_waitcnt lgkmcnt(0)
	v_mfma_f32_16x16x32_bf16 v[138:141], v[172:175], v[206:209], v[138:141]
	ds_read_b128 v[172:175], v165 offset:2048
	s_waitcnt lgkmcnt(0)
	v_mfma_f32_16x16x32_bf16 v[118:121], v[172:175], v[176:179], v[118:121]
	v_mfma_f32_16x16x32_bf16 v[102:105], v[172:175], v[198:201], v[102:105]
	v_mfma_f32_16x16x32_bf16 v[106:109], v[172:175], v[202:205], v[106:109]
	v_mfma_f32_16x16x32_bf16 v[114:117], v[172:175], v[206:209], v[114:117]
	ds_read_b128 v[172:175], v165 offset:4096
	s_waitcnt lgkmcnt(0)
	v_mfma_f32_16x16x32_bf16 v[110:113], v[172:175], v[176:179], v[110:113]
	v_mfma_f32_16x16x32_bf16 v[122:125], v[172:175], v[198:201], v[122:125]
	v_mfma_f32_16x16x32_bf16 v[134:137], v[172:175], v[202:205], v[134:137]
	v_mfma_f32_16x16x32_bf16 v[130:133], v[172:175], v[206:209], v[130:133]
	ds_read_b128 v[172:175], v165 offset:6144
	s_waitcnt lgkmcnt(0)
	v_mfma_f32_16x16x32_bf16 v[98:101], v[172:175], v[176:179], v[98:101]
	ds_read_b128 v[176:179], v0
	v_mfma_f32_16x16x32_bf16 v[158:161], v[172:175], v[198:201], v[158:161]
	ds_read_b128 v[198:201], v163 offset:18432
	v_mfma_f32_16x16x32_bf16 v[154:157], v[172:175], v[202:205], v[154:157]
	ds_read_b128 v[202:205], v163 offset:20480
	v_mfma_f32_16x16x32_bf16 v[150:153], v[172:175], v[206:209], v[150:153]
	ds_read_b128 v[172:175], v163 offset:16384
	ds_read_b128 v[206:209], v163 offset:22528
	s_waitcnt lgkmcnt(1)
	v_mfma_f32_16x16x32_bf16 v[126:129], v[176:179], v[172:175], v[126:129]
	v_mfma_f32_16x16x32_bf16 v[146:149], v[176:179], v[198:201], v[146:149]
	v_mfma_f32_16x16x32_bf16 v[142:145], v[176:179], v[202:205], v[142:145]
	s_waitcnt lgkmcnt(0)
	v_mfma_f32_16x16x32_bf16 v[138:141], v[176:179], v[206:209], v[138:141]
	ds_read_b128 v[176:179], v0 offset:2048
	s_waitcnt lgkmcnt(0)
	v_mfma_f32_16x16x32_bf16 v[118:121], v[176:179], v[172:175], v[118:121]
	v_mfma_f32_16x16x32_bf16 v[102:105], v[176:179], v[198:201], v[102:105]
	v_mfma_f32_16x16x32_bf16 v[106:109], v[176:179], v[202:205], v[106:109]
	v_mfma_f32_16x16x32_bf16 v[114:117], v[176:179], v[206:209], v[114:117]
	ds_read_b128 v[176:179], v0 offset:4096
	s_waitcnt lgkmcnt(0)
	v_mfma_f32_16x16x32_bf16 v[110:113], v[176:179], v[172:175], v[110:113]
	v_mfma_f32_16x16x32_bf16 v[122:125], v[176:179], v[198:201], v[122:125]
	v_mfma_f32_16x16x32_bf16 v[134:137], v[176:179], v[202:205], v[134:137]
	v_mfma_f32_16x16x32_bf16 v[130:133], v[176:179], v[206:209], v[130:133]
	ds_read_b128 v[176:179], v0 offset:6144
	s_waitcnt vmcnt(15)
	ds_write_b128 v167, v[66:69] offset:32768
	s_waitcnt vmcnt(14)
	ds_write_b128 v167, v[70:73] offset:49152
	s_waitcnt vmcnt(13)
	ds_write_b128 v167, v[74:77] offset:36864
	s_waitcnt vmcnt(12)
	ds_write_b128 v167, v[78:81] offset:53248
	s_waitcnt vmcnt(11)
	ds_write_b128 v167, v[82:85] offset:40960
	s_waitcnt vmcnt(10)
	ds_write_b128 v167, v[86:89] offset:57344
	s_waitcnt vmcnt(9)
	ds_write_b128 v167, v[90:93] offset:45056
	s_waitcnt vmcnt(8)
	ds_write_b128 v167, v[94:97] offset:61440
	s_waitcnt lgkmcnt(0)
	s_barrier
	ds_read_b128 v[66:69], v165 offset:32768
	ds_read_b128 v[74:77], v170 offset:49152
	s_waitcnt lgkmcnt(0)
	v_mfma_f32_16x16x32_bf16 v[78:81], v[66:69], v[74:77], v[126:129]
	ds_read_b128 v[82:85], v170 offset:51200
	ds_read_b128 v[90:93], v170 offset:53248
	s_nop 0
	ds_read_b128 v[126:129], v170 offset:55296
	s_waitcnt lgkmcnt(2)
	v_mfma_f32_16x16x32_bf16 v[86:89], v[66:69], v[82:85], v[146:149]
	ds_read_b128 v[168:171], v163 offset:51200
	s_waitcnt lgkmcnt(2)
	v_mfma_f32_16x16x32_bf16 v[94:97], v[66:69], v[90:93], v[142:145]
	s_waitcnt lgkmcnt(1)
	v_mfma_f32_16x16x32_bf16 v[66:69], v[66:69], v[126:129], v[138:141]
	s_nop 2
	ds_read_b128 v[138:141], v165 offset:34816
	s_waitcnt lgkmcnt(0)
	v_mfma_f32_16x16x32_bf16 v[142:145], v[138:141], v[90:93], v[106:109]
	s_nop 2
	ds_read_b128 v[106:109], v165 offset:36864
	v_mfma_f32_16x16x32_bf16 v[118:121], v[138:141], v[74:77], v[118:121]
	v_mfma_f32_16x16x32_bf16 v[102:105], v[138:141], v[82:85], v[102:105]
	v_mfma_f32_16x16x32_bf16 v[114:117], v[138:141], v[126:129], v[114:117]
	s_waitcnt lgkmcnt(0)
	v_mfma_f32_16x16x32_bf16 v[138:141], v[106:109], v[74:77], v[110:113]
	v_mfma_f32_16x16x32_bf16 v[146:149], v[106:109], v[82:85], v[122:125]
	v_mfma_f32_16x16x32_bf16 v[134:137], v[106:109], v[90:93], v[134:137]
	v_mfma_f32_16x16x32_bf16 v[130:133], v[106:109], v[126:129], v[130:133]
	ds_read_b128 v[106:109], v165 offset:38912
	v_mfma_f32_16x16x32_bf16 v[98:101], v[176:179], v[172:175], v[98:101]
	ds_read_b128 v[172:175], v163 offset:53248
	v_mfma_f32_16x16x32_bf16 v[158:161], v[176:179], v[198:201], v[158:161]
	s_waitcnt lgkmcnt(1)
	v_mfma_f32_16x16x32_bf16 v[98:101], v[106:109], v[74:77], v[98:101]
	ds_read_b128 v[74:77], v0 offset:32768
	v_mfma_f32_16x16x32_bf16 v[154:157], v[176:179], v[202:205], v[154:157]
	v_mfma_f32_16x16x32_bf16 v[70:73], v[176:179], v[206:209], v[150:153]
	ds_read_b128 v[176:179], v163 offset:55296
	v_mfma_f32_16x16x32_bf16 v[82:85], v[106:109], v[82:85], v[158:161]
	s_nop 2
	ds_read_b128 v[158:161], v163 offset:49152
	v_mfma_f32_16x16x32_bf16 v[150:153], v[106:109], v[90:93], v[154:157]
	v_mfma_f32_16x16x32_bf16 v[154:157], v[106:109], v[126:129], v[70:73]
	s_waitcnt lgkmcnt(0)
	v_mfma_f32_16x16x32_bf16 v[126:129], v[74:77], v[158:161], v[78:81]
	v_mfma_f32_16x16x32_bf16 v[78:81], v[74:77], v[176:179], v[66:69]
	s_nop 2
	ds_read_b128 v[66:69], v0 offset:34816
	v_mfma_f32_16x16x32_bf16 v[110:113], v[74:77], v[168:171], v[86:89]
	v_mfma_f32_16x16x32_bf16 v[94:97], v[74:77], v[172:175], v[94:97]
	s_waitcnt lgkmcnt(0)
	v_mfma_f32_16x16x32_bf16 v[122:125], v[66:69], v[158:161], v[118:121]
	v_mfma_f32_16x16x32_bf16 v[106:109], v[66:69], v[168:171], v[102:105]
	v_mfma_f32_16x16x32_bf16 v[90:93], v[66:69], v[172:175], v[142:145]
	v_mfma_f32_16x16x32_bf16 v[74:77], v[66:69], v[176:179], v[114:117]
	ds_read_b128 v[66:69], v0 offset:36864
	s_waitcnt lgkmcnt(0)
	v_mfma_f32_16x16x32_bf16 v[118:121], v[66:69], v[158:161], v[138:141]
	v_mfma_f32_16x16x32_bf16 v[102:105], v[66:69], v[168:171], v[146:149]
	v_mfma_f32_16x16x32_bf16 v[86:89], v[66:69], v[172:175], v[134:137]
	s_nop 1
	v_mov_b32_e32 v146, v180
	v_mfma_f32_16x16x32_bf16 v[70:73], v[66:69], v[176:179], v[130:133]
	ds_read_b128 v[66:69], v0 offset:38912
	s_waitcnt lgkmcnt(0)
	s_barrier
	v_mfma_f32_16x16x32_bf16 v[114:117], v[66:69], v[158:161], v[98:101]
	v_mfma_f32_16x16x32_bf16 v[98:101], v[66:69], v[168:171], v[82:85]
	v_mfma_f32_16x16x32_bf16 v[82:85], v[66:69], v[172:175], v[150:153]
	v_mfma_f32_16x16x32_bf16 v[66:69], v[66:69], v[176:179], v[154:157]
	s_cbranch_vccnz .LBB0_262
	s_cmp_lt_u32 s20, 18
	s_cbranch_scc1 .LBB0_263
	s_cmp_eq_u32 s20, 18
	s_cbranch_scc1 .LBB0_264
	s_cmp_lt_u32 s20, 27
	s_mov_b64 s[6:7], 0
	s_cbranch_scc1 .LBB0_856
	s_cmp_lt_u32 s20, 35
	s_mov_b64 s[8:9], 0
	s_cbranch_scc1 .LBB0_857
	s_cmp_lt_u32 s20, 43
	s_mov_b64 s[10:11], 0
	s_cbranch_scc1 .LBB0_862
	s_cmp_lt_u32 s20, 51
	s_cbranch_scc1 .LBB0_865
	s_cmp_lt_u32 s20, 59
	s_mov_b64 s[42:43], 0
	s_cbranch_scc1 .LBB0_866
	s_cmpk_lt_u32 s20, 0x43
	s_mov_b64 s[46:47], 0
	s_cbranch_scc1 .LBB0_867
	s_cmpk_lt_u32 s20, 0x4b
	s_cselect_b64 s[72:73], -1, 0
	s_cmpk_gt_u32 s20, 0x4a
	s_cselect_b64 s[34:35], -1, 0
	s_and_b64 s[28:29], s[72:73], exec
	s_movk_i32 s28, 0xffbd
	s_cselect_b32 s38, s28, 0xffffffb5
	s_movk_i32 s28, 0x1900
	s_cselect_b32 s28, s28, 0x1d00
	s_branch .LBB0_864

.LBB0_932:
	s_andn2_b64 vcc, exec, s[6:7]
	s_cbranch_vccnz .LBB0_934
	v_readlane_b32 s6, v254, 58
	s_cmp_lg_u32 s6, 0
	s_mov_b64 s[4:5], -1
	s_mov_b64 s[8:9], -1
